# speedup vs baseline: 1.0052x; 1.0052x over previous
; template <bool OUT>
; __device__ __forceinline__ void ssm_fast(KArgs ap, int l, LAS unsigned char* lds, const Ctx cx) {
;     ...
;         for (int sc = 0; sc < 4; ++sc) {
;             const size_t tk = tok0 + sc * 32;
;             const bf16x8 uf = *(const bf16x8*)(z + (tk + r) * DIN + ZS + g * 16 + 8 * hh);
.LBB0_170:
	s_lshl_b32 s76, s5, 5
	v_lshl_add_u64 v[0:1], v[90:91], 0, s[76:77]
	v_mov_b64_e32 v[2:3], s[0:1]
	s_movk_i32 s7, 0x1600
	v_mad_u64_u32 v[2:3], s[10:11], v0, s7, v[2:3]
	v_mad_i32_i24 v3, v1, s7, v3
	s_mov_b32 s7, s77
	v_lshl_add_u64 v[0:1], v[2:3], 0, s[6:7]
	v_lshl_add_u64 v[0:1], v[84:85], 1, v[0:1]
	v_add_co_u32_e32 v0, vcc, 0x13000000, v0
	s_nop 0
	s_nop 0
	v_addc_co_u32_e32 v1, vcc, 0, v1, vcc
	s_cmp_lg_u32 s5, 0
	s_cbranch_scc1 .Lssma_have_u
	global_load_dwordx4 v[102:105], v[0:1], off offset:2560

; __device__ __forceinline__ unsigned cvt_pk_bf16(float lo, float hi) { unsigned r; asm volatile("v_cvt_pk_bf16_f32 %0, %1, %2" : "=v"(r) : "v"(lo), "v"(hi)); return r; }
;     __device__ __forceinline__ void operator()(const f32x4 (&acc)[2][2][4][2], const Unit& u, int wr, int wc, int fr, int fq) const {
;     ...
;                 for (int bj = 0; bj < 2; ++bj) xv[m][bj] = *(const u32x4*)(X + (size_t)(row0 + ai * HALF + m * 16) * ldc + col0 + bj * HALF);
;             asm volatile("" ::: "memory");
; #pragma unroll
;             for (int m = 0; m < 4; ++m) { const int row = row0 + ai * HALF + m * 16; bf16_t* rowp = X + (size_t)row * ldc + col0;
;                 float part = 0.f;
; #pragma unroll
;                 for (int bj = 0; bj < 2; ++bj) { const u32x4 x4 = xv[m][bj];
;                     const f32x4 a0 = acc[ai][bj][m][0], a1 = acc[ai][bj][m][1];
;                     const float f0 = bflo(x4.x) + a0[0], f1 = bfhi(x4.x) + a0[1], f2 = bflo(x4.y) + a0[2], f3 = bfhi(x4.y) + a0[3];
;                     const float f4 = bflo(x4.z) + a1[0], f5 = bfhi(x4.z) + a1[1], f6 = bflo(x4.w) + a1[2], f7 = bfhi(x4.w) + a1[3];
;                     part += (f0 * f0 + f1 * f1) + (f2 * f2 + f3 * f3) + (f4 * f4 + f5 * f5) + (f6 * f6 + f7 * f7);
;                     u32x4 w; w.x = cvt_pk_bf16(f0, f1); w.y = cvt_pk_bf16(f2, f3); w.z = cvt_pk_bf16(f4, f5); w.w = cvt_pk_bf16(f6, f7);
;                     *(u32x4*)(rowp + bj * HALF) = w; }
;                 part += __shfl_xor(part, 16); part += __shfl_xor(part, 32);
;                 if (fq == 0) SS[(size_t)row * 32 + u.pn * 4 + wc] = part; }
.LBB0_561:
	s_or_b64 exec, exec, s[4:5]
	v_add_u32_e32 v98, 0x80, v184
	v_ashrrev_i32_e32 v99, 31, v98
	v_lshlrev_b64 v[100:101], 12, v[98:99]
	s_waitcnt lgkmcnt(0)
	v_lshl_add_u64 v[64:65], v[182:183], 0, v[100:101]
	s_waitcnt vmcnt(12)
	v_mov_b64_e32 v[102:103], v[222:223]
	v_mov_b64_e32 v[104:105], v[224:225]
	v_mov_b64_e32 v[88:89], v[226:227]
	v_mov_b64_e32 v[90:91], v[228:229]
	v_add_u32_e32 v96, 0x90, v184
	v_ashrrev_i32_e32 v97, 31, v96
	v_lshlrev_b64 v[64:65], 12, v[96:97]
	v_add_u32_e32 v94, 0xa0, v184
	v_lshl_add_u64 v[64:65], v[182:183], 0, v[64:65]
	v_ashrrev_i32_e32 v95, 31, v94
	v_mov_b64_e32 v[84:85], v[230:231]
	v_mov_b64_e32 v[86:87], v[232:233]
	v_mov_b64_e32 v[80:81], v[234:235]
	v_mov_b64_e32 v[82:83], v[236:237]
	v_lshlrev_b64 v[64:65], 12, v[94:95]
	v_add_u32_e32 v92, 0xb0, v184
	v_lshl_add_u64 v[64:65], v[182:183], 0, v[64:65]
	v_ashrrev_i32_e32 v93, 31, v92
	v_mov_b64_e32 v[76:77], v[238:239]
	v_mov_b64_e32 v[78:79], v[240:241]
	v_mov_b64_e32 v[72:73], v[244:245]
	v_mov_b64_e32 v[74:75], v[246:247]
	v_lshlrev_b64 v[64:65], 12, v[92:93]
	v_lshl_add_u64 v[64:65], v[182:183], 0, v[64:65]
	v_mov_b64_e32 v[68:69], v[248:249]
	v_mov_b64_e32 v[70:71], v[250:251]
	s_nop 0
	v_mov_b64_e32 v[64:65], v[252:253]
	v_mov_b64_e32 v[66:67], v[254:255]
	v_lshl_add_u64 v[100:101], s[8:9], 0, v[100:101]
	v_lshl_add_u64 v[100:101], v[180:181], 1, v[100:101]
	s_nop 0
	v_lshlrev_b32_e32 v106, 16, v102
	v_and_b32_e32 v102, 0xffff0000, v102
	v_add_f32_e32 v61, v61, v102
	v_lshlrev_b32_e32 v102, 16, v103
	v_add_f32_e32 v62, v62, v102
	v_and_b32_e32 v102, 0xffff0000, v103
	v_add_f32_e32 v63, v63, v102
	v_lshlrev_b32_e32 v102, 16, v104
	v_add_f32_e32 v102, v56, v102
	v_and_b32_e32 v56, 0xffff0000, v104
	v_add_f32_e32 v103, v57, v56
	v_lshlrev_b32_e32 v56, 16, v105
	v_add_f32_e32 v104, v58, v56
	v_and_b32_e32 v56, 0xffff0000, v105
	v_add_f32_e32 v60, v60, v106
	v_add_f32_e32 v59, v59, v56
	v_mul_f32_e32 v56, v61, v61
	v_mul_f32_e32 v57, v63, v63
	v_fmac_f32_e32 v56, v60, v60
	v_fmac_f32_e32 v57, v62, v62
	v_add_f32_e32 v56, v56, v57
	v_mul_f32_e32 v57, v103, v103
	v_fmac_f32_e32 v57, v102, v102
	v_add_f32_e32 v56, v57, v56
	v_mul_f32_e32 v57, v59, v59
	v_fmac_f32_e32 v57, v104, v104
	v_add_f32_e32 v105, v57, v56
	v_cvt_pk_bf16_f32 v56, v60, v61
	v_cvt_pk_bf16_f32 v57, v62, v63
	v_cvt_pk_bf16_f32 v58, v102, v103
	v_cvt_pk_bf16_f32 v59, v104, v59
	global_store_dwordx4 v[100:101], v[56:59], off
	s_nop 0
	s_nop 0
	v_lshlrev_b32_e32 v56, 16, v88
	v_add_f32_e32 v52, v52, v56
	v_and_b32_e32 v56, 0xffff0000, v88
	v_add_f32_e32 v53, v53, v56
	v_lshlrev_b32_e32 v56, 16, v89
	v_add_f32_e32 v54, v54, v56
	v_and_b32_e32 v56, 0xffff0000, v89
	v_add_f32_e32 v55, v55, v56
	v_lshlrev_b32_e32 v56, 16, v90
	v_add_f32_e32 v56, v48, v56
	v_and_b32_e32 v48, 0xffff0000, v90
	v_add_f32_e32 v57, v49, v48
	v_lshlrev_b32_e32 v48, 16, v91
	v_add_f32_e32 v58, v50, v48
	v_and_b32_e32 v48, 0xffff0000, v91
	v_add_f32_e32 v51, v51, v48
	v_mul_f32_e32 v48, v53, v53
	v_mul_f32_e32 v49, v55, v55
	v_fmac_f32_e32 v48, v52, v52
	v_fmac_f32_e32 v49, v54, v54
	v_add_f32_e32 v48, v48, v49
	v_mul_f32_e32 v49, v57, v57
	v_fmac_f32_e32 v49, v56, v56
	v_add_f32_e32 v48, v49, v48
	v_mul_f32_e32 v49, v51, v51
	v_fmac_f32_e32 v49, v58, v58
	v_add_f32_e32 v48, v49, v48
	v_add_f32_e32 v59, v105, v48
	v_cvt_pk_bf16_f32 v48, v52, v53
	v_cvt_pk_bf16_f32 v49, v54, v55
	v_cvt_pk_bf16_f32 v50, v56, v57
	v_cvt_pk_bf16_f32 v51, v58, v51
	global_store_dwordx4 v[100:101], v[48:51], off offset:256
	ds_bpermute_b32 v48, v112, v59
	s_waitcnt lgkmcnt(0)
	v_add_f32_e32 v48, v59, v48
	ds_bpermute_b32 v49, v113, v48
	s_and_saveexec_b64 s[4:5], vcc
	s_cbranch_execz .LBB0_563
	v_lshlrev_b64 v[50:51], 7, v[98:99]
	v_lshl_add_u64 v[50:51], s[10:11], 0, v[50:51]
	v_lshl_add_u64 v[50:51], s[22:23], 2, v[50:51]
	s_lshl_b32 s76, s61, 2
	v_lshl_add_u64 v[50:51], v[50:51], 0, s[76:77]
	s_waitcnt lgkmcnt(0)
	v_add_f32_e32 v48, v48, v49
	global_store_dword v[50:51], v48, off
.LBB0_563:
	s_or_b64 exec, exec, s[4:5]
	s_nop 0
	v_lshlrev_b32_e32 v50, 16, v84
	v_add_f32_e32 v44, v44, v50
	v_and_b32_e32 v50, 0xffff0000, v84
	v_add_f32_e32 v45, v45, v50
	v_lshlrev_b32_e32 v50, 16, v85
	v_add_f32_e32 v46, v46, v50
	v_and_b32_e32 v50, 0xffff0000, v85
	v_add_f32_e32 v47, v47, v50
	v_lshlrev_b32_e32 v50, 16, v86
	v_add_f32_e32 v50, v40, v50
	v_and_b32_e32 v40, 0xffff0000, v86
	v_add_f32_e32 v51, v41, v40
	v_lshlrev_b32_e32 v40, 16, v87
	v_add_f32_e32 v52, v42, v40
	v_and_b32_e32 v40, 0xffff0000, v87
	v_add_f32_e32 v43, v43, v40
	v_mul_f32_e32 v40, v45, v45
	v_mul_f32_e32 v41, v47, v47
	v_fmac_f32_e32 v40, v44, v44
	v_fmac_f32_e32 v41, v46, v46
	v_add_f32_e32 v40, v40, v41
	v_mul_f32_e32 v41, v51, v51
	v_fmac_f32_e32 v41, v50, v50
	v_add_f32_e32 v40, v41, v40
	v_mul_f32_e32 v41, v43, v43
	v_fmac_f32_e32 v41, v52, v52
	v_add_f32_e32 v42, v41, v40
	v_cvt_pk_bf16_f32 v40, v44, v45
	s_nop 0
	v_lshlrev_b32_e32 v44, 16, v80
	v_add_f32_e32 v36, v36, v44
	v_and_b32_e32 v44, 0xffff0000, v80
	v_add_f32_e32 v37, v37, v44
	v_lshlrev_b32_e32 v44, 16, v81
	v_add_f32_e32 v38, v38, v44
	v_and_b32_e32 v44, 0xffff0000, v81
	v_add_f32_e32 v39, v39, v44
	v_lshlrev_b32_e32 v44, 16, v82
	v_add_f32_e32 v44, v32, v44
	v_and_b32_e32 v32, 0xffff0000, v82
	v_add_f32_e32 v45, v33, v32
	v_lshlrev_b32_e32 v32, 16, v83
	v_cvt_pk_bf16_f32 v41, v46, v47
	v_add_f32_e32 v46, v34, v32
	v_and_b32_e32 v32, 0xffff0000, v83
	v_add_f32_e32 v47, v35, v32
	v_mul_f32_e32 v32, v37, v37
	v_mul_f32_e32 v33, v39, v39
	v_fmac_f32_e32 v32, v36, v36
	v_fmac_f32_e32 v33, v38, v38
	v_add_f32_e32 v32, v32, v33
	v_mul_f32_e32 v33, v45, v45
	v_fmac_f32_e32 v33, v44, v44
	v_add_f32_e32 v32, v33, v32
	v_mul_f32_e32 v33, v47, v47
	v_fmac_f32_e32 v33, v46, v46
	v_add_f32_e32 v32, v33, v32
	v_add_f32_e32 v32, v42, v32
	ds_bpermute_b32 v33, v112, v32
	s_waitcnt lgkmcnt(1)
	v_lshlrev_b64 v[48:49], 11, v[96:97]
	v_lshl_add_u64 v[48:49], v[48:49], 1, s[8:9]
	v_lshl_add_u64 v[48:49], v[180:181], 1, v[48:49]
	v_cvt_pk_bf16_f32 v42, v50, v51
	s_waitcnt lgkmcnt(0)
	v_add_f32_e32 v32, v32, v33
	ds_bpermute_b32 v33, v113, v32
	v_cvt_pk_bf16_f32 v43, v52, v43
	global_store_dwordx4 v[48:49], v[40:43], off
	v_cvt_pk_bf16_f32 v34, v36, v37
	v_cvt_pk_bf16_f32 v35, v38, v39
	v_cvt_pk_bf16_f32 v36, v44, v45
	v_cvt_pk_bf16_f32 v37, v46, v47
	global_store_dwordx4 v[48:49], v[34:37], off offset:256
	s_and_saveexec_b64 s[4:5], vcc
	s_cbranch_execz .LBB0_565
	v_lshlrev_b64 v[34:35], 7, v[96:97]
	v_lshl_add_u64 v[34:35], s[10:11], 0, v[34:35]
	v_lshl_add_u64 v[34:35], s[22:23], 2, v[34:35]
	s_lshl_b32 s76, s61, 2
	v_lshl_add_u64 v[34:35], v[34:35], 0, s[76:77]
	s_waitcnt lgkmcnt(0)
	v_add_f32_e32 v32, v32, v33
	global_store_dword v[34:35], v32, off
; __device__ __forceinline__ unsigned cvt_pk_bf16(float lo, float hi) { unsigned r; asm volatile("v_cvt_pk_bf16_f32 %0, %1, %2" : "=v"(r) : "v"(lo), "v"(hi)); return r; }
;     __device__ __forceinline__ void operator()(const f32x4 (&acc)[2][2][4][2], const Unit& u, int wr, int wc, int fr, int fq) const {
;     ...
;             for (int m = 0; m < 4; ++m) { const int row = row0 + ai * HALF + m * 16; bf16_t* rowp = X + (size_t)row * ldc + col0;
;                 float part = 0.f;
; #pragma unroll
;                 for (int bj = 0; bj < 2; ++bj) { const u32x4 x4 = xv[m][bj];
;                     const f32x4 a0 = acc[ai][bj][m][0], a1 = acc[ai][bj][m][1];
;                     const float f0 = bflo(x4.x) + a0[0], f1 = bfhi(x4.x) + a0[1], f2 = bflo(x4.y) + a0[2], f3 = bfhi(x4.y) + a0[3];
;                     const float f4 = bflo(x4.z) + a1[0], f5 = bfhi(x4.z) + a1[1], f6 = bflo(x4.w) + a1[2], f7 = bfhi(x4.w) + a1[3];
;                     part += (f0 * f0 + f1 * f1) + (f2 * f2 + f3 * f3) + (f4 * f4 + f5 * f5) + (f6 * f6 + f7 * f7);
;                     u32x4 w; w.x = cvt_pk_bf16(f0, f1); w.y = cvt_pk_bf16(f2, f3); w.z = cvt_pk_bf16(f4, f5); w.w = cvt_pk_bf16(f6, f7);
;                     *(u32x4*)(rowp + bj * HALF) = w; }
;                 part += __shfl_xor(part, 16); part += __shfl_xor(part, 32);
;                 if (fq == 0) SS[(size_t)row * 32 + u.pn * 4 + wc] = part; }
.LBB0_565:
	s_or_b64 exec, exec, s[4:5]
	s_nop 0
	v_lshlrev_b32_e32 v34, 16, v76
	v_add_f32_e32 v28, v28, v34
	v_and_b32_e32 v34, 0xffff0000, v76
	v_add_f32_e32 v29, v29, v34
	v_lshlrev_b32_e32 v34, 16, v77
	v_add_f32_e32 v30, v30, v34
	v_and_b32_e32 v34, 0xffff0000, v77
	v_add_f32_e32 v31, v31, v34
	v_lshlrev_b32_e32 v34, 16, v78
	v_add_f32_e32 v34, v24, v34
	v_and_b32_e32 v24, 0xffff0000, v78
	v_add_f32_e32 v35, v25, v24
	v_lshlrev_b32_e32 v24, 16, v79
	v_add_f32_e32 v36, v26, v24
	v_and_b32_e32 v24, 0xffff0000, v79
	v_add_f32_e32 v27, v27, v24
	v_mul_f32_e32 v24, v29, v29
	v_mul_f32_e32 v25, v31, v31
	v_fmac_f32_e32 v24, v28, v28
	v_fmac_f32_e32 v25, v30, v30
	v_add_f32_e32 v24, v24, v25
	v_mul_f32_e32 v25, v35, v35
	v_fmac_f32_e32 v25, v34, v34
	v_add_f32_e32 v24, v25, v24
	v_mul_f32_e32 v25, v27, v27
	v_fmac_f32_e32 v25, v36, v36
	v_add_f32_e32 v26, v25, v24
	v_cvt_pk_bf16_f32 v24, v28, v29
	s_nop 0
	v_lshlrev_b32_e32 v28, 16, v72
	v_add_f32_e32 v20, v20, v28
	v_and_b32_e32 v28, 0xffff0000, v72
	v_add_f32_e32 v21, v21, v28
	v_lshlrev_b32_e32 v28, 16, v73
	v_add_f32_e32 v22, v22, v28
	v_and_b32_e32 v28, 0xffff0000, v73
	v_add_f32_e32 v23, v23, v28
	v_lshlrev_b32_e32 v28, 16, v74
	v_add_f32_e32 v28, v16, v28
	v_and_b32_e32 v16, 0xffff0000, v74
	v_add_f32_e32 v29, v17, v16
	v_lshlrev_b32_e32 v16, 16, v75
	v_cvt_pk_bf16_f32 v25, v30, v31
	v_add_f32_e32 v30, v18, v16
	v_and_b32_e32 v16, 0xffff0000, v75
	v_add_f32_e32 v31, v19, v16
	v_mul_f32_e32 v16, v21, v21
	v_mul_f32_e32 v17, v23, v23
	v_fmac_f32_e32 v16, v20, v20
	v_fmac_f32_e32 v17, v22, v22
	v_add_f32_e32 v16, v16, v17
	v_mul_f32_e32 v17, v29, v29
	v_fmac_f32_e32 v17, v28, v28
	v_add_f32_e32 v16, v17, v16
	v_mul_f32_e32 v17, v31, v31
	v_fmac_f32_e32 v17, v30, v30
	v_add_f32_e32 v16, v17, v16
	v_add_f32_e32 v16, v26, v16
	ds_bpermute_b32 v17, v112, v16
	s_waitcnt lgkmcnt(1)
	v_lshlrev_b64 v[32:33], 11, v[94:95]
	v_lshl_add_u64 v[32:33], v[32:33], 1, s[8:9]
	v_lshl_add_u64 v[32:33], v[180:181], 1, v[32:33]
	v_cvt_pk_bf16_f32 v26, v34, v35
	s_waitcnt lgkmcnt(0)
	v_add_f32_e32 v16, v16, v17
	ds_bpermute_b32 v17, v113, v16
	v_cvt_pk_bf16_f32 v27, v36, v27
	global_store_dwordx4 v[32:33], v[24:27], off
	v_cvt_pk_bf16_f32 v18, v20, v21
	v_cvt_pk_bf16_f32 v19, v22, v23
	v_cvt_pk_bf16_f32 v20, v28, v29
	v_cvt_pk_bf16_f32 v21, v30, v31
	global_store_dwordx4 v[32:33], v[18:21], off offset:256
	s_and_saveexec_b64 s[4:5], vcc
	s_cbranch_execz .LBB0_567
	v_lshlrev_b64 v[18:19], 7, v[94:95]
	v_lshl_add_u64 v[18:19], s[10:11], 0, v[18:19]
	v_lshl_add_u64 v[18:19], s[22:23], 2, v[18:19]
	s_lshl_b32 s76, s61, 2
	v_lshl_add_u64 v[18:19], v[18:19], 0, s[76:77]
	s_waitcnt lgkmcnt(0)
	v_add_f32_e32 v16, v16, v17
	global_store_dword v[18:19], v16, off
.LBB0_567:
	s_or_b64 exec, exec, s[4:5]
	s_nop 0
	v_lshlrev_b32_e32 v18, 16, v68
	v_add_f32_e32 v12, v12, v18
	v_and_b32_e32 v18, 0xffff0000, v68
	v_add_f32_e32 v13, v13, v18
	v_lshlrev_b32_e32 v18, 16, v69
	v_add_f32_e32 v14, v14, v18
	v_and_b32_e32 v18, 0xffff0000, v69
	v_add_f32_e32 v15, v15, v18
	v_lshlrev_b32_e32 v18, 16, v70
	v_add_f32_e32 v18, v8, v18
	v_and_b32_e32 v8, 0xffff0000, v70
	v_add_f32_e32 v19, v9, v8
	v_lshlrev_b32_e32 v8, 16, v71
	v_add_f32_e32 v20, v10, v8
	v_and_b32_e32 v8, 0xffff0000, v71
	v_add_f32_e32 v11, v11, v8
	v_mul_f32_e32 v8, v13, v13
	v_mul_f32_e32 v9, v15, v15
	v_fmac_f32_e32 v8, v12, v12
	v_fmac_f32_e32 v9, v14, v14
	v_add_f32_e32 v8, v8, v9
	v_mul_f32_e32 v9, v19, v19
	v_fmac_f32_e32 v9, v18, v18
	v_add_f32_e32 v8, v9, v8
	v_mul_f32_e32 v9, v11, v11
	v_fmac_f32_e32 v9, v20, v20
	v_add_f32_e32 v10, v9, v8
	v_cvt_pk_bf16_f32 v8, v12, v13
	s_nop 0
	v_lshlrev_b32_e32 v12, 16, v64
	v_add_f32_e32 v4, v4, v12
	v_and_b32_e32 v12, 0xffff0000, v64
	v_add_f32_e32 v5, v5, v12
	v_lshlrev_b32_e32 v12, 16, v65
	v_add_f32_e32 v6, v6, v12
	v_and_b32_e32 v12, 0xffff0000, v65
	v_add_f32_e32 v7, v7, v12
	v_lshlrev_b32_e32 v12, 16, v66
	v_add_f32_e32 v12, v0, v12
	v_and_b32_e32 v0, 0xffff0000, v66
	v_add_f32_e32 v13, v1, v0
	v_lshlrev_b32_e32 v0, 16, v67
	v_cvt_pk_bf16_f32 v9, v14, v15
	v_add_f32_e32 v14, v2, v0
	v_and_b32_e32 v0, 0xffff0000, v67
	v_add_f32_e32 v15, v3, v0
	v_mul_f32_e32 v0, v5, v5
	v_mul_f32_e32 v1, v7, v7
	v_fmac_f32_e32 v0, v4, v4
	v_fmac_f32_e32 v1, v6, v6
	v_add_f32_e32 v0, v0, v1
	v_mul_f32_e32 v1, v13, v13
	v_fmac_f32_e32 v1, v12, v12
	v_add_f32_e32 v0, v1, v0
	v_mul_f32_e32 v1, v15, v15
	v_fmac_f32_e32 v1, v14, v14
	v_add_f32_e32 v0, v1, v0
	v_add_f32_e32 v0, v10, v0
	ds_bpermute_b32 v1, v112, v0
	s_waitcnt lgkmcnt(1)
	v_lshlrev_b64 v[16:17], 11, v[92:93]
	v_lshl_add_u64 v[16:17], v[16:17], 1, s[8:9]
	v_lshl_add_u64 v[16:17], v[180:181], 1, v[16:17]
	v_cvt_pk_bf16_f32 v10, v18, v19
	s_waitcnt lgkmcnt(0)
	v_add_f32_e32 v0, v0, v1
	ds_bpermute_b32 v1, v113, v0
	v_cvt_pk_bf16_f32 v11, v20, v11
	global_store_dwordx4 v[16:17], v[8:11], off
	v_cvt_pk_bf16_f32 v2, v4, v5
	v_cvt_pk_bf16_f32 v3, v6, v7
	v_cvt_pk_bf16_f32 v4, v12, v13
	v_cvt_pk_bf16_f32 v5, v14, v15
	global_store_dwordx4 v[16:17], v[2:5], off offset:256
	s_and_saveexec_b64 s[4:5], vcc
	s_cbranch_execz .LBB0_569
	v_lshlrev_b64 v[2:3], 7, v[92:93]
	v_lshl_add_u64 v[2:3], s[10:11], 0, v[2:3]
	v_lshl_add_u64 v[2:3], s[22:23], 2, v[2:3]
	s_lshl_b32 s76, s61, 2
	v_lshl_add_u64 v[2:3], v[2:3], 0, s[76:77]
	s_waitcnt lgkmcnt(0)
	v_add_f32_e32 v0, v0, v1
	global_store_dword v[2:3], v0, off

; __device__ __forceinline__ unsigned cvt_pk_bf16(float lo, float hi) { unsigned r; asm volatile("v_cvt_pk_bf16_f32 %0, %1, %2" : "=v"(r) : "v"(lo), "v"(hi)); return r; }
;     __device__ __forceinline__ void operator()(const f32x4 (&acc)[2][2][4][2], const Unit& u, int wr, int wc, int fr, int fq) const {
;     ...
;                 for (int bj = 0; bj < 2; ++bj) xv[m][bj] = *(const u32x4*)(X + (size_t)(row0 + ai * HALF + m * 16) * ldc + col0 + bj * HALF);
;             asm volatile("" ::: "memory");
; #pragma unroll
;             for (int m = 0; m < 4; ++m) { const int row = row0 + ai * HALF + m * 16; bf16_t* rowp = X + (size_t)row * ldc + col0;
;                 float part = 0.f;
; #pragma unroll
;                 for (int bj = 0; bj < 2; ++bj) { const u32x4 x4 = xv[m][bj];
;                     const f32x4 a0 = acc[ai][bj][m][0], a1 = acc[ai][bj][m][1];
;                     const float f0 = bflo(x4.x) + a0[0], f1 = bfhi(x4.x) + a0[1], f2 = bflo(x4.y) + a0[2], f3 = bfhi(x4.y) + a0[3];
;                     const float f4 = bflo(x4.z) + a1[0], f5 = bfhi(x4.z) + a1[1], f6 = bflo(x4.w) + a1[2], f7 = bfhi(x4.w) + a1[3];
;                     part += (f0 * f0 + f1 * f1) + (f2 * f2 + f3 * f3) + (f4 * f4 + f5 * f5) + (f6 * f6 + f7 * f7);
;                     u32x4 w; w.x = cvt_pk_bf16(f0, f1); w.y = cvt_pk_bf16(f2, f3); w.z = cvt_pk_bf16(f4, f5); w.w = cvt_pk_bf16(f6, f7);
;                     *(u32x4*)(rowp + bj * HALF) = w; }
;                 part += __shfl_xor(part, 16); part += __shfl_xor(part, 32);
;                 if (fq == 0) SS[(size_t)row * 32 + u.pn * 4 + wc] = part; }
.LBB0_774:
	s_or_b64 exec, exec, s[4:5]
	v_add_u32_e32 v98, 0x80, v184
	v_ashrrev_i32_e32 v99, 31, v98
	v_lshlrev_b64 v[100:101], 12, v[98:99]
	s_waitcnt lgkmcnt(0)
	v_lshl_add_u64 v[64:65], v[182:183], 0, v[100:101]
	s_waitcnt vmcnt(12)
	v_mov_b64_e32 v[102:103], v[222:223]
	v_mov_b64_e32 v[104:105], v[224:225]
	v_mov_b64_e32 v[88:89], v[226:227]
	v_mov_b64_e32 v[90:91], v[228:229]
	v_add_u32_e32 v96, 0x90, v184
	v_ashrrev_i32_e32 v97, 31, v96
	v_lshlrev_b64 v[64:65], 12, v[96:97]
	v_add_u32_e32 v94, 0xa0, v184
	v_lshl_add_u64 v[64:65], v[182:183], 0, v[64:65]
	v_ashrrev_i32_e32 v95, 31, v94
	v_mov_b64_e32 v[84:85], v[230:231]
	v_mov_b64_e32 v[86:87], v[232:233]
	v_mov_b64_e32 v[80:81], v[234:235]
	v_mov_b64_e32 v[82:83], v[236:237]
	v_lshlrev_b64 v[64:65], 12, v[94:95]
	v_add_u32_e32 v92, 0xb0, v184
	v_lshl_add_u64 v[64:65], v[182:183], 0, v[64:65]
	v_ashrrev_i32_e32 v93, 31, v92
	v_mov_b64_e32 v[76:77], v[238:239]
	v_mov_b64_e32 v[78:79], v[240:241]
	v_mov_b64_e32 v[72:73], v[244:245]
	v_mov_b64_e32 v[74:75], v[246:247]
	v_lshlrev_b64 v[64:65], 12, v[92:93]
	v_lshl_add_u64 v[64:65], v[182:183], 0, v[64:65]
	v_mov_b64_e32 v[68:69], v[248:249]
	v_mov_b64_e32 v[70:71], v[250:251]
	s_nop 0
	v_mov_b64_e32 v[64:65], v[252:253]
	v_mov_b64_e32 v[66:67], v[254:255]
	v_lshl_add_u64 v[100:101], s[8:9], 0, v[100:101]
	v_lshl_add_u64 v[100:101], v[180:181], 1, v[100:101]
	s_nop 0
	v_lshlrev_b32_e32 v106, 16, v102
	v_and_b32_e32 v102, 0xffff0000, v102
	v_add_f32_e32 v61, v61, v102
	v_lshlrev_b32_e32 v102, 16, v103
	v_add_f32_e32 v62, v62, v102
	v_and_b32_e32 v102, 0xffff0000, v103
	v_add_f32_e32 v63, v63, v102
	v_lshlrev_b32_e32 v102, 16, v104
	v_add_f32_e32 v102, v56, v102
	v_and_b32_e32 v56, 0xffff0000, v104
	v_add_f32_e32 v103, v57, v56
	v_lshlrev_b32_e32 v56, 16, v105
	v_add_f32_e32 v104, v58, v56
	v_and_b32_e32 v56, 0xffff0000, v105
	v_add_f32_e32 v60, v60, v106
	v_add_f32_e32 v59, v59, v56
	v_mul_f32_e32 v56, v61, v61
	v_mul_f32_e32 v57, v63, v63
	v_fmac_f32_e32 v56, v60, v60
	v_fmac_f32_e32 v57, v62, v62
	v_add_f32_e32 v56, v56, v57
	v_mul_f32_e32 v57, v103, v103
	v_fmac_f32_e32 v57, v102, v102
	v_add_f32_e32 v56, v57, v56
	v_mul_f32_e32 v57, v59, v59
	v_fmac_f32_e32 v57, v104, v104
	v_add_f32_e32 v105, v57, v56
	v_cvt_pk_bf16_f32 v56, v60, v61
	v_cvt_pk_bf16_f32 v57, v62, v63
	v_cvt_pk_bf16_f32 v58, v102, v103
	v_cvt_pk_bf16_f32 v59, v104, v59
	global_store_dwordx4 v[100:101], v[56:59], off
	s_nop 0
	s_nop 0
	v_lshlrev_b32_e32 v56, 16, v88
	v_add_f32_e32 v52, v52, v56
	v_and_b32_e32 v56, 0xffff0000, v88
	v_add_f32_e32 v53, v53, v56
	v_lshlrev_b32_e32 v56, 16, v89
	v_add_f32_e32 v54, v54, v56
	v_and_b32_e32 v56, 0xffff0000, v89
	v_add_f32_e32 v55, v55, v56
	v_lshlrev_b32_e32 v56, 16, v90
	v_add_f32_e32 v56, v48, v56
	v_and_b32_e32 v48, 0xffff0000, v90
	v_add_f32_e32 v57, v49, v48
	v_lshlrev_b32_e32 v48, 16, v91
	v_add_f32_e32 v58, v50, v48
	v_and_b32_e32 v48, 0xffff0000, v91
	v_add_f32_e32 v51, v51, v48
	v_mul_f32_e32 v48, v53, v53
	v_mul_f32_e32 v49, v55, v55
	v_fmac_f32_e32 v48, v52, v52
	v_fmac_f32_e32 v49, v54, v54
	v_add_f32_e32 v48, v48, v49
	v_mul_f32_e32 v49, v57, v57
	v_fmac_f32_e32 v49, v56, v56
	v_add_f32_e32 v48, v49, v48
	v_mul_f32_e32 v49, v51, v51
	v_fmac_f32_e32 v49, v58, v58
	v_add_f32_e32 v48, v49, v48
	v_add_f32_e32 v59, v105, v48
	v_cvt_pk_bf16_f32 v48, v52, v53
	v_cvt_pk_bf16_f32 v49, v54, v55
	v_cvt_pk_bf16_f32 v50, v56, v57
	v_cvt_pk_bf16_f32 v51, v58, v51
	global_store_dwordx4 v[100:101], v[48:51], off offset:256
	ds_bpermute_b32 v48, v112, v59
	s_waitcnt lgkmcnt(0)
	v_add_f32_e32 v48, v59, v48
	ds_bpermute_b32 v49, v113, v48
	s_and_saveexec_b64 s[4:5], vcc
	s_cbranch_execz .LBB0_776
	v_lshlrev_b64 v[50:51], 7, v[98:99]
	v_lshl_add_u64 v[50:51], s[10:11], 0, v[50:51]
	v_lshl_add_u64 v[50:51], s[18:19], 2, v[50:51]
	s_lshl_b32 s76, s55, 2
	v_lshl_add_u64 v[50:51], v[50:51], 0, s[76:77]
	s_waitcnt lgkmcnt(0)
	v_add_f32_e32 v48, v48, v49
	global_store_dword v[50:51], v48, off
.LBB0_776:
	s_or_b64 exec, exec, s[4:5]
	s_nop 0
	v_lshlrev_b32_e32 v50, 16, v84
	v_add_f32_e32 v44, v44, v50
	v_and_b32_e32 v50, 0xffff0000, v84
	v_add_f32_e32 v45, v45, v50
	v_lshlrev_b32_e32 v50, 16, v85
	v_add_f32_e32 v46, v46, v50
	v_and_b32_e32 v50, 0xffff0000, v85
	v_add_f32_e32 v47, v47, v50
	v_lshlrev_b32_e32 v50, 16, v86
	v_add_f32_e32 v50, v40, v50
	v_and_b32_e32 v40, 0xffff0000, v86
	v_add_f32_e32 v51, v41, v40
	v_lshlrev_b32_e32 v40, 16, v87
	v_add_f32_e32 v52, v42, v40
	v_and_b32_e32 v40, 0xffff0000, v87
	v_add_f32_e32 v43, v43, v40
	v_mul_f32_e32 v40, v45, v45
	v_mul_f32_e32 v41, v47, v47
	v_fmac_f32_e32 v40, v44, v44
	v_fmac_f32_e32 v41, v46, v46
	v_add_f32_e32 v40, v40, v41
	v_mul_f32_e32 v41, v51, v51
	v_fmac_f32_e32 v41, v50, v50
	v_add_f32_e32 v40, v41, v40
	v_mul_f32_e32 v41, v43, v43
	v_fmac_f32_e32 v41, v52, v52
	v_add_f32_e32 v42, v41, v40
	v_cvt_pk_bf16_f32 v40, v44, v45
	s_nop 0
	v_lshlrev_b32_e32 v44, 16, v80
	v_add_f32_e32 v36, v36, v44
	v_and_b32_e32 v44, 0xffff0000, v80
	v_add_f32_e32 v37, v37, v44
	v_lshlrev_b32_e32 v44, 16, v81
	v_add_f32_e32 v38, v38, v44
	v_and_b32_e32 v44, 0xffff0000, v81
	v_add_f32_e32 v39, v39, v44
	v_lshlrev_b32_e32 v44, 16, v82
	v_add_f32_e32 v44, v32, v44
	v_and_b32_e32 v32, 0xffff0000, v82
	v_add_f32_e32 v45, v33, v32
	v_lshlrev_b32_e32 v32, 16, v83
	v_cvt_pk_bf16_f32 v41, v46, v47
	v_add_f32_e32 v46, v34, v32
	v_and_b32_e32 v32, 0xffff0000, v83
	v_add_f32_e32 v47, v35, v32
	v_mul_f32_e32 v32, v37, v37
	v_mul_f32_e32 v33, v39, v39
	v_fmac_f32_e32 v32, v36, v36
	v_fmac_f32_e32 v33, v38, v38
	v_add_f32_e32 v32, v32, v33
	v_mul_f32_e32 v33, v45, v45
	v_fmac_f32_e32 v33, v44, v44
	v_add_f32_e32 v32, v33, v32
	v_mul_f32_e32 v33, v47, v47
	v_fmac_f32_e32 v33, v46, v46
	v_add_f32_e32 v32, v33, v32
	v_add_f32_e32 v32, v42, v32
	ds_bpermute_b32 v33, v112, v32
	s_waitcnt lgkmcnt(1)
	v_lshlrev_b64 v[48:49], 11, v[96:97]
	v_lshl_add_u64 v[48:49], v[48:49], 1, s[8:9]
	v_lshl_add_u64 v[48:49], v[180:181], 1, v[48:49]
	v_cvt_pk_bf16_f32 v42, v50, v51
	s_waitcnt lgkmcnt(0)
	v_add_f32_e32 v32, v32, v33
	ds_bpermute_b32 v33, v113, v32
	v_cvt_pk_bf16_f32 v43, v52, v43
	global_store_dwordx4 v[48:49], v[40:43], off
	v_cvt_pk_bf16_f32 v34, v36, v37
	v_cvt_pk_bf16_f32 v35, v38, v39
	v_cvt_pk_bf16_f32 v36, v44, v45
	v_cvt_pk_bf16_f32 v37, v46, v47
	global_store_dwordx4 v[48:49], v[34:37], off offset:256
	s_and_saveexec_b64 s[4:5], vcc
	s_cbranch_execz .LBB0_778
	v_lshlrev_b64 v[34:35], 7, v[96:97]
	v_lshl_add_u64 v[34:35], s[10:11], 0, v[34:35]
	v_lshl_add_u64 v[34:35], s[18:19], 2, v[34:35]
	s_lshl_b32 s76, s55, 2
	v_lshl_add_u64 v[34:35], v[34:35], 0, s[76:77]
	s_waitcnt lgkmcnt(0)
	v_add_f32_e32 v32, v32, v33
	global_store_dword v[34:35], v32, off
; __device__ __forceinline__ unsigned cvt_pk_bf16(float lo, float hi) { unsigned r; asm volatile("v_cvt_pk_bf16_f32 %0, %1, %2" : "=v"(r) : "v"(lo), "v"(hi)); return r; }
;     __device__ __forceinline__ void operator()(const f32x4 (&acc)[2][2][4][2], const Unit& u, int wr, int wc, int fr, int fq) const {
;     ...
;             for (int m = 0; m < 4; ++m) { const int row = row0 + ai * HALF + m * 16; bf16_t* rowp = X + (size_t)row * ldc + col0;
;                 float part = 0.f;
; #pragma unroll
;                 for (int bj = 0; bj < 2; ++bj) { const u32x4 x4 = xv[m][bj];
;                     const f32x4 a0 = acc[ai][bj][m][0], a1 = acc[ai][bj][m][1];
;                     const float f0 = bflo(x4.x) + a0[0], f1 = bfhi(x4.x) + a0[1], f2 = bflo(x4.y) + a0[2], f3 = bfhi(x4.y) + a0[3];
;                     const float f4 = bflo(x4.z) + a1[0], f5 = bfhi(x4.z) + a1[1], f6 = bflo(x4.w) + a1[2], f7 = bfhi(x4.w) + a1[3];
;                     part += (f0 * f0 + f1 * f1) + (f2 * f2 + f3 * f3) + (f4 * f4 + f5 * f5) + (f6 * f6 + f7 * f7);
;                     u32x4 w; w.x = cvt_pk_bf16(f0, f1); w.y = cvt_pk_bf16(f2, f3); w.z = cvt_pk_bf16(f4, f5); w.w = cvt_pk_bf16(f6, f7);
;                     *(u32x4*)(rowp + bj * HALF) = w; }
;                 part += __shfl_xor(part, 16); part += __shfl_xor(part, 32);
;                 if (fq == 0) SS[(size_t)row * 32 + u.pn * 4 + wc] = part; }
.LBB0_778:
	s_or_b64 exec, exec, s[4:5]
	s_nop 0
	v_lshlrev_b32_e32 v34, 16, v76
	v_add_f32_e32 v28, v28, v34
	v_and_b32_e32 v34, 0xffff0000, v76
	v_add_f32_e32 v29, v29, v34
	v_lshlrev_b32_e32 v34, 16, v77
	v_add_f32_e32 v30, v30, v34
	v_and_b32_e32 v34, 0xffff0000, v77
	v_add_f32_e32 v31, v31, v34
	v_lshlrev_b32_e32 v34, 16, v78
	v_add_f32_e32 v34, v24, v34
	v_and_b32_e32 v24, 0xffff0000, v78
	v_add_f32_e32 v35, v25, v24
	v_lshlrev_b32_e32 v24, 16, v79
	v_add_f32_e32 v36, v26, v24
	v_and_b32_e32 v24, 0xffff0000, v79
	v_add_f32_e32 v27, v27, v24
	v_mul_f32_e32 v24, v29, v29
	v_mul_f32_e32 v25, v31, v31
	v_fmac_f32_e32 v24, v28, v28
	v_fmac_f32_e32 v25, v30, v30
	v_add_f32_e32 v24, v24, v25
	v_mul_f32_e32 v25, v35, v35
	v_fmac_f32_e32 v25, v34, v34
	v_add_f32_e32 v24, v25, v24
	v_mul_f32_e32 v25, v27, v27
	v_fmac_f32_e32 v25, v36, v36
	v_add_f32_e32 v26, v25, v24
	v_cvt_pk_bf16_f32 v24, v28, v29
	s_nop 0
	v_lshlrev_b32_e32 v28, 16, v72
	v_add_f32_e32 v20, v20, v28
	v_and_b32_e32 v28, 0xffff0000, v72
	v_add_f32_e32 v21, v21, v28
	v_lshlrev_b32_e32 v28, 16, v73
	v_add_f32_e32 v22, v22, v28
	v_and_b32_e32 v28, 0xffff0000, v73
	v_add_f32_e32 v23, v23, v28
	v_lshlrev_b32_e32 v28, 16, v74
	v_add_f32_e32 v28, v16, v28
	v_and_b32_e32 v16, 0xffff0000, v74
	v_add_f32_e32 v29, v17, v16
	v_lshlrev_b32_e32 v16, 16, v75
	v_cvt_pk_bf16_f32 v25, v30, v31
	v_add_f32_e32 v30, v18, v16
	v_and_b32_e32 v16, 0xffff0000, v75
	v_add_f32_e32 v31, v19, v16
	v_mul_f32_e32 v16, v21, v21
	v_mul_f32_e32 v17, v23, v23
	v_fmac_f32_e32 v16, v20, v20
	v_fmac_f32_e32 v17, v22, v22
	v_add_f32_e32 v16, v16, v17
	v_mul_f32_e32 v17, v29, v29
	v_fmac_f32_e32 v17, v28, v28
	v_add_f32_e32 v16, v17, v16
	v_mul_f32_e32 v17, v31, v31
	v_fmac_f32_e32 v17, v30, v30
	v_add_f32_e32 v16, v17, v16
	v_add_f32_e32 v16, v26, v16
	ds_bpermute_b32 v17, v112, v16
	s_waitcnt lgkmcnt(1)
	v_lshlrev_b64 v[32:33], 11, v[94:95]
	v_lshl_add_u64 v[32:33], v[32:33], 1, s[8:9]
	v_lshl_add_u64 v[32:33], v[180:181], 1, v[32:33]
	v_cvt_pk_bf16_f32 v26, v34, v35
	s_waitcnt lgkmcnt(0)
	v_add_f32_e32 v16, v16, v17
	ds_bpermute_b32 v17, v113, v16
	v_cvt_pk_bf16_f32 v27, v36, v27
	global_store_dwordx4 v[32:33], v[24:27], off
	v_cvt_pk_bf16_f32 v18, v20, v21
	v_cvt_pk_bf16_f32 v19, v22, v23
	v_cvt_pk_bf16_f32 v20, v28, v29
	v_cvt_pk_bf16_f32 v21, v30, v31
	global_store_dwordx4 v[32:33], v[18:21], off offset:256
	s_and_saveexec_b64 s[4:5], vcc
	s_cbranch_execz .LBB0_780
	v_lshlrev_b64 v[18:19], 7, v[94:95]
	v_lshl_add_u64 v[18:19], s[10:11], 0, v[18:19]
	v_lshl_add_u64 v[18:19], s[18:19], 2, v[18:19]
	s_lshl_b32 s76, s55, 2
	v_lshl_add_u64 v[18:19], v[18:19], 0, s[76:77]
	s_waitcnt lgkmcnt(0)
	v_add_f32_e32 v16, v16, v17
	global_store_dword v[18:19], v16, off
.LBB0_780:
	s_or_b64 exec, exec, s[4:5]
	s_nop 0
	v_lshlrev_b32_e32 v18, 16, v68
	v_add_f32_e32 v12, v12, v18
	v_and_b32_e32 v18, 0xffff0000, v68
	v_add_f32_e32 v13, v13, v18
	v_lshlrev_b32_e32 v18, 16, v69
	v_add_f32_e32 v14, v14, v18
	v_and_b32_e32 v18, 0xffff0000, v69
	v_add_f32_e32 v15, v15, v18
	v_lshlrev_b32_e32 v18, 16, v70
	v_add_f32_e32 v18, v8, v18
	v_and_b32_e32 v8, 0xffff0000, v70
	v_add_f32_e32 v19, v9, v8
	v_lshlrev_b32_e32 v8, 16, v71
	v_add_f32_e32 v20, v10, v8
	v_and_b32_e32 v8, 0xffff0000, v71
	v_add_f32_e32 v11, v11, v8
	v_mul_f32_e32 v8, v13, v13
	v_mul_f32_e32 v9, v15, v15
	v_fmac_f32_e32 v8, v12, v12
	v_fmac_f32_e32 v9, v14, v14
	v_add_f32_e32 v8, v8, v9
	v_mul_f32_e32 v9, v19, v19
	v_fmac_f32_e32 v9, v18, v18
	v_add_f32_e32 v8, v9, v8
	v_mul_f32_e32 v9, v11, v11
	v_fmac_f32_e32 v9, v20, v20
	v_add_f32_e32 v10, v9, v8
	v_cvt_pk_bf16_f32 v8, v12, v13
	s_nop 0
	v_lshlrev_b32_e32 v12, 16, v64
	v_add_f32_e32 v4, v4, v12
	v_and_b32_e32 v12, 0xffff0000, v64
	v_add_f32_e32 v5, v5, v12
	v_lshlrev_b32_e32 v12, 16, v65
	v_add_f32_e32 v6, v6, v12
	v_and_b32_e32 v12, 0xffff0000, v65
	v_add_f32_e32 v7, v7, v12
	v_lshlrev_b32_e32 v12, 16, v66
	v_add_f32_e32 v12, v0, v12
	v_and_b32_e32 v0, 0xffff0000, v66
	v_add_f32_e32 v13, v1, v0
	v_lshlrev_b32_e32 v0, 16, v67
	v_cvt_pk_bf16_f32 v9, v14, v15
	v_add_f32_e32 v14, v2, v0
	v_and_b32_e32 v0, 0xffff0000, v67
	v_add_f32_e32 v15, v3, v0
	v_mul_f32_e32 v0, v5, v5
	v_mul_f32_e32 v1, v7, v7
	v_fmac_f32_e32 v0, v4, v4
	v_fmac_f32_e32 v1, v6, v6
	v_add_f32_e32 v0, v0, v1
	v_mul_f32_e32 v1, v13, v13
	v_fmac_f32_e32 v1, v12, v12
	v_add_f32_e32 v0, v1, v0
	v_mul_f32_e32 v1, v15, v15
	v_fmac_f32_e32 v1, v14, v14
	v_add_f32_e32 v0, v1, v0
	v_add_f32_e32 v0, v10, v0
	ds_bpermute_b32 v1, v112, v0
	s_waitcnt lgkmcnt(1)
	v_lshlrev_b64 v[16:17], 11, v[92:93]
	v_lshl_add_u64 v[16:17], v[16:17], 1, s[8:9]
	v_lshl_add_u64 v[16:17], v[180:181], 1, v[16:17]
	v_cvt_pk_bf16_f32 v10, v18, v19
	s_waitcnt lgkmcnt(0)
	v_add_f32_e32 v0, v0, v1
	ds_bpermute_b32 v1, v113, v0
	v_cvt_pk_bf16_f32 v11, v20, v11
	global_store_dwordx4 v[16:17], v[8:11], off
	v_cvt_pk_bf16_f32 v2, v4, v5
	v_cvt_pk_bf16_f32 v3, v6, v7
	v_cvt_pk_bf16_f32 v4, v12, v13
	v_cvt_pk_bf16_f32 v5, v14, v15
	global_store_dwordx4 v[16:17], v[2:5], off offset:256
	s_and_saveexec_b64 s[4:5], vcc
	s_cbranch_execz .LBB0_782
	v_lshlrev_b64 v[2:3], 7, v[92:93]
	v_lshl_add_u64 v[2:3], s[10:11], 0, v[2:3]
	v_lshl_add_u64 v[2:3], s[18:19], 2, v[2:3]
	s_lshl_b32 s76, s55, 2
	v_lshl_add_u64 v[2:3], v[2:3], 0, s[76:77]
	s_waitcnt lgkmcnt(0)
	v_add_f32_e32 v0, v0, v1
	global_store_dword v[2:3], v0, off
